# v109 + transpose loops: loop-top waits exclude the previous tile's store (counted vmcnt 2/1), first tile waited in the preheader
# speedup vs baseline: 1.0044x; 1.0044x over previous
.Lks_none:
	s_waitcnt lgkmcnt(0)
	s_and_b32 s6, s6, 15
	v_writelane_b32 v255, s6, 62
	v_and_b32_e32 v4, 60, v1
	v_add_u32_e32 v2, s0, v17
	v_ashrrev_i32_e32 v3, 31, v2
	v_readlane_b32 s0, v253, 51
	v_lshlrev_b64 v[2:3], 14, v[2:3]
	v_readlane_b32 s1, v253, 52
	v_lshlrev_b32_e32 v176, 2, v4
	v_ashrrev_i32_e32 v32, 3, v0
	v_lshl_add_u64 v[2:3], s[0:1], 0, v[2:3]
	v_lshl_add_u64 v[2:3], v[2:3], 0, v[176:177]
	v_add_co_u32_e32 v6, vcc, 0x80000, v2
	s_movk_i32 s0, 0x104
	s_nop 0
	v_addc_co_u32_e32 v7, vcc, 0, v3, vcc
	global_load_dwordx4 v[8:11], v[2:3], off
	global_load_dwordx4 v[12:15], v[6:7], off
	v_lshlrev_b32_e32 v0, 3, v0
	v_mul_lo_u32 v1, v17, s0
	v_and_b32_e32 v16, 56, v0
	v_add3_u32 v25, 0, v1, v176
	v_lshl_add_u32 v0, v32, 2, 0
	v_xor_b32_e32 v33, 32, v32
	v_mul_u32_u24_e32 v1, 0x104, v16
	v_cmp_lt_i32_e64 s[42:43], 32, v32
	v_mad_u32_u24 v34, v16, s0, 0
	v_lshlrev_b32_e32 v35, 1, v33
	v_lshlrev_b32_e32 v36, 1, v32
	v_lshlrev_b32_e32 v18, 2, v4
	v_add_u32_e32 v37, v0, v1
	s_mov_b32 s3, s96
	s_waitcnt vmcnt(0)
	s_branch .LBB0_343
